# baseline (speedup 1.0000x reference)
; __device__ __forceinline__ void qkt8(f32x16& p0, f32x16& p1, const char* Ks, const i32x8* qf, int r32, int hi) {
;   p0 = f32x16{}; p1 = f32x16{};
;   const char* kb = Ks + r32 * K8ROW + hi * 32;
;   i32x8 a0 = ld32B(kb), a1 = ld32B(kb + 32 * K8ROW);
;   i32x8 b0 = ld32B(kb + 64), b1 = ld32B(kb + 32 * K8ROW + 64);
;   p0 = mfma8(a0, qf[0], p0); p1 = mfma8(a1, qf[0], p1);
;   a0 = ld32B(kb + 128); a1 = ld32B(kb + 32 * K8ROW + 128);
;   p0 = mfma8(b0, qf[1], p0); p1 = mfma8(b1, qf[1], p1);
;   p0 = mfma8(a0, qf[2], p0); p1 = mfma8(a1, qf[2], p1);
; }
; __device__ __forceinline__ void pv8(f32x16* o, f32x16& lacc, const char* Vs, i32x8 pf, int r32, int hi) {
;   const char* vb = Vs + r32 * V8ROW + hi * 32;
; #pragma unroll
;   for (int d0 = 0; d0 < 4; ++d0) o[d0] = mfma8(pf, ld32B(vb + d0 * 32 * V8ROW), o[d0]);
;   const int one4 = 0x38383838;
;   lacc = mfma8(pf, i32x8{one4, one4, one4, one4, one4, one4, one4, one4}, lacc);
; }
; __device__ __forceinline__ void partialSM8(f32x16& p0, f32x16& p1, float& m_reg, float& mn, float& alpha) {
;   float pmax = p0[0];
; #pragma unroll
;   for (int r = 1; r < 16; ++r) pmax = fmaxf(pmax, p0[r]);
; #pragma unroll
;   for (int r = 0; r < 16; ++r) pmax = fmaxf(pmax, p1[r]);
;   { auto rr = __builtin_amdgcn_permlane32_swap(__float_as_uint(pmax), __float_as_uint(pmax), false, false);
;     pmax = fmaxf(__uint_as_float(rr[0]), __uint_as_float(rr[1])); }
;   if (__builtin_expect(__all(pmax - m_reg <= THR8 * 8.f * 1.4426950408889634f), 1)) { mn = m_reg; alpha = 1.f; }
;   else { mn = fmaxf(m_reg, pmax); alpha = __builtin_amdgcn_exp2f((m_reg - mn) * 0.125f); m_reg = mn; }
;   const float mn8 = (P8SHIFT + 7.f - 0.0436f) * 8.f + 0.5f - mn;
; #pragma unroll
;   for (int r = 0; r < 16; ++r) p0[r] += mn8;
; #pragma unroll
;   for (int r = 0; r < 16; ++r) p1[r] += mn8;
; }
; __device__ __forceinline__ unsigned pk4u8(float a, float b, float c, float d) {
;   unsigned w = __builtin_amdgcn_cvt_pk_u8_f32(a, 0u, 0u); w = __builtin_amdgcn_cvt_pk_u8_f32(b, 1u, w);
;   w = __builtin_amdgcn_cvt_pk_u8_f32(c, 2u, w); return __builtin_amdgcn_cvt_pk_u8_f32(d, 3u, w);
; }
; __device__ __forceinline__ void finishSM8(f32x16& p0, f32x16& p1, i32x8& pf) {
; #pragma unroll
;   for (int w = 0; w < 4; ++w) { pf[w] = (int)pk4u8(p0[4 * w], p0[4 * w + 1], p0[4 * w + 2], p0[4 * w + 3]);
.LBB0_912:
	s_mul_i32 s2, s22, 0x3400
	v_add_u32_e32 v113, s2, v214
	ds_read_b128 v[80:83], v113 offset:51200
	ds_read_b128 v[84:87], v113 offset:51216
	s_waitcnt lgkmcnt(0)
	v_mfma_scale_f32_32x32x64_f8f6f4 v[96:111], v[80:87], v[120:127], 0, v193, v193 op_sel_hi:[0,0,0]
	ds_read_b128 v[80:83], v113 offset:57856
	ds_read_b128 v[84:87], v113 offset:57872
	ds_read_b128 v[218:221], v113 offset:51264
	ds_read_b128 v[222:225], v113 offset:51280
	s_waitcnt lgkmcnt(2)
	v_mfma_scale_f32_32x32x64_f8f6f4 v[80:95], v[80:87], v[120:127], 0, v193, v193 op_sel_hi:[0,0,0]
	s_waitcnt lgkmcnt(0)
	v_mfma_scale_f32_32x32x64_f8f6f4 v[96:111], v[218:225], v[128:135], v[96:111], v193, v193 op_sel_hi:[0,0,0]
	ds_read_b128 v[218:221], v113 offset:57920
	ds_read_b128 v[222:225], v113 offset:57936
	ds_read_b128 v[226:229], v113 offset:51328
	ds_read_b128 v[230:233], v113 offset:51344
	ds_read_b128 v[234:237], v113 offset:57984
	ds_read_b128 v[238:241], v113 offset:58000
	v_cvt_pk_u8_f32 v113, v184, 0, 0
	v_cvt_pk_u8_f32 v113, v185, 1, v113
	v_cvt_pk_u8_f32 v113, v182, 2, v113
	s_waitcnt lgkmcnt(4)
	v_mfma_scale_f32_32x32x64_f8f6f4 v[80:95], v[218:225], v[128:135], v[80:95], v193, v193 op_sel_hi:[0,0,0]
	v_cvt_pk_u8_f32 v218, v183, 3, v113
	v_cvt_pk_u8_f32 v113, v198, 0, 0
	v_cvt_pk_u8_f32 v113, v199, 1, v113
	v_cvt_pk_u8_f32 v113, v196, 2, v113
	v_cvt_pk_u8_f32 v222, v197, 3, v113
	v_cvt_pk_u8_f32 v113, v178, 0, 0
	v_cvt_pk_u8_f32 v113, v179, 1, v113
	v_cvt_pk_u8_f32 v113, v174, 2, v113
	v_cvt_pk_u8_f32 v219, v175, 3, v113
	v_cvt_pk_u8_f32 v113, v194, 0, 0
	v_cvt_pk_u8_f32 v113, v195, 1, v113
	v_cvt_pk_u8_f32 v113, v190, 2, v113
	v_cvt_pk_u8_f32 v223, v191, 3, v113
	v_cvt_pk_u8_f32 v113, v172, 0, 0
	v_cvt_pk_u8_f32 v113, v173, 1, v113
	s_waitcnt lgkmcnt(2)
	v_mfma_scale_f32_32x32x64_f8f6f4 v[96:111], v[226:233], v[136:143], v[96:111], v193, v193 op_sel_hi:[0,0,0]
	v_cvt_pk_u8_f32 v113, v118, 2, v113
	v_cvt_pk_u8_f32 v220, v119, 3, v113
	v_cvt_pk_u8_f32 v113, v188, 0, 0
	v_cvt_pk_u8_f32 v113, v189, 1, v113
	v_cvt_pk_u8_f32 v113, v186, 2, v113
	v_cvt_pk_u8_f32 v224, v187, 3, v113
	v_cvt_pk_u8_f32 v113, v116, 0, 0
	v_cvt_pk_u8_f32 v113, v117, 1, v113
	v_cvt_pk_u8_f32 v113, v114, 2, v113
	v_cvt_pk_u8_f32 v221, v115, 3, v113
	v_cvt_pk_u8_f32 v113, v180, 0, 0
	v_cvt_pk_u8_f32 v113, v181, 1, v113
	v_cvt_pk_u8_f32 v113, v176, 2, v113
	v_cvt_pk_u8_f32 v225, v177, 3, v113
	s_waitcnt lgkmcnt(0)
	v_mfma_scale_f32_32x32x64_f8f6f4 v[80:95], v[234:241], v[136:143], v[80:95], v193, v193 op_sel_hi:[0,0,0]
	s_mul_i32 s2, s21, 0x2800
	s_addk_i32 s2, 0xd800
	s_cmp_lg_u32 s21, 0
	s_cselect_b32 s2, s2, 0xa000
	v_add_u32_e32 v113, s2, v217
	ds_read_b128 v[172:175], v113
	ds_read_b128 v[176:179], v113 offset:16
	v_max_f32_e32 v188, v96, v97
	v_max3_f32 v188, v188, v98, v99
	s_waitcnt lgkmcnt(0)
	v_mfma_scale_f32_32x32x64_f8f6f4 v[48:63], v[218:225], v[172:179], v[48:63], v193, v193 op_sel_hi:[0,0,0]
	ds_read_b128 v[172:175], v113 offset:2560
	ds_read_b128 v[176:179], v113 offset:2576
	s_waitcnt lgkmcnt(0)
	v_mfma_scale_f32_32x32x64_f8f6f4 v[32:47], v[218:225], v[172:179], v[32:47], v193, v193 op_sel_hi:[0,0,0]
	ds_read_b128 v[172:175], v113 offset:5120
	ds_read_b128 v[176:179], v113 offset:5136
	ds_read_b128 v[180:183], v113 offset:7680
	ds_read_b128 v[184:187], v113 offset:7696
	s_waitcnt lgkmcnt(2)
	v_mfma_scale_f32_32x32x64_f8f6f4 v[16:31], v[218:225], v[172:179], v[16:31], v193, v193 op_sel_hi:[0,0,0]
	v_max3_f32 v172, v188, v100, v101
	v_max3_f32 v172, v172, v102, v103
	v_max3_f32 v172, v172, v104, v105
	v_max3_f32 v172, v172, v106, v107
	v_max3_f32 v172, v172, v108, v109
	v_max3_f32 v172, v172, v110, v111
	v_max3_f32 v172, v172, v80, v81
	v_max3_f32 v172, v172, v82, v83
	v_max3_f32 v172, v172, v84, v85
	v_max3_f32 v172, v172, v86, v87
	v_max3_f32 v172, v172, v88, v89
	v_max3_f32 v172, v172, v90, v91
	v_max3_f32 v172, v172, v92, v93
	v_max3_f32 v172, v172, v94, v95
	v_mov_b32_e32 v173, v172
	s_waitcnt lgkmcnt(0)
	v_mfma_scale_f32_32x32x64_f8f6f4 v[0:15], v[218:225], v[180:187], v[0:15], v193, v193 op_sel_hi:[0,0,0]
	v_permlane32_swap_b32_e32 v172, v173
	v_max_f32_e32 v172, v172, v173
	v_sub_f32_e32 v173, v172, v216
	v_cmp_ge_f32_e32 vcc, s61, v173
	v_mfma_scale_f32_16x16x128_f8f6f4 v[64:67], v[218:225], v[244:251], v[64:67], v193, v193 op_sel_hi:[0,0,0]
	s_cmp_eq_u64 vcc, exec
	s_cselect_b64 s[10:11], -1, 0
	s_cbranch_scc1 .LBB0_916
	v_max_f32_e32 v172, v216, v172
	v_sub_f32_e32 v174, v216, v172
	v_mul_f32_e32 v174, 0x3e000000, v174
	v_exp_f32_e32 v174, v174
	s_nop 0
	v_mov_b32_e32 v173, v174
	v_cmp_gt_f32_e32 vcc, 1.0, v173
	s_cbranch_vccz .LBB0_916
	s_and_saveexec_b64 s[16:17], s[8:9]
	ds_write_b32 v215, v173 offset:128
	s_or_b64 exec, exec, s[16:17]
	s_waitcnt lgkmcnt(0)
	v_add_u32_e32 v113, v159, v213
	ds_read_b128 v[114:117], v113 offset:224
	ds_read_b128 v[174:177], v113 offset:192
	ds_read_b128 v[178:181], v113 offset:160
	ds_read_b128 v[182:185], v113 offset:128
	s_waitcnt lgkmcnt(3)
	v_pk_mul_f32 v[60:61], v[60:61], v[114:115]
	s_waitcnt lgkmcnt(2)
	v_pk_mul_f32 v[56:57], v[56:57], v[174:175]
	s_waitcnt lgkmcnt(1)
	v_pk_mul_f32 v[52:53], v[52:53], v[178:179]
	v_pk_mul_f32 v[62:63], v[62:63], v[116:117]
	v_pk_mul_f32 v[58:59], v[58:59], v[176:177]
	v_pk_mul_f32 v[54:55], v[54:55], v[180:181]
	s_waitcnt lgkmcnt(0)
	v_pk_mul_f32 v[50:51], v[50:51], v[184:185]
	v_pk_mul_f32 v[48:49], v[48:49], v[182:183]
	v_pk_mul_f32 v[44:45], v[44:45], v[114:115]
	v_pk_mul_f32 v[40:41], v[40:41], v[174:175]
	v_pk_mul_f32 v[36:37], v[36:37], v[178:179]
	v_pk_mul_f32 v[46:47], v[46:47], v[116:117]
	v_pk_mul_f32 v[42:43], v[42:43], v[176:177]
	v_pk_mul_f32 v[38:39], v[38:39], v[180:181]
	v_pk_mul_f32 v[34:35], v[34:35], v[184:185]
	v_pk_mul_f32 v[32:33], v[32:33], v[182:183]
	v_pk_mul_f32 v[28:29], v[28:29], v[114:115]
	v_pk_mul_f32 v[24:25], v[24:25], v[174:175]
	v_pk_mul_f32 v[20:21], v[20:21], v[178:179]
	v_pk_mul_f32 v[30:31], v[30:31], v[116:117]
	v_pk_mul_f32 v[26:27], v[26:27], v[176:177]
	v_pk_mul_f32 v[22:23], v[22:23], v[180:181]
	v_pk_mul_f32 v[18:19], v[18:19], v[184:185]
	v_pk_mul_f32 v[16:17], v[16:17], v[182:183]
	v_pk_mul_f32 v[12:13], v[12:13], v[114:115]
	v_pk_mul_f32 v[8:9], v[8:9], v[174:175]
	v_pk_mul_f32 v[4:5], v[4:5], v[178:179]
	v_pk_mul_f32 v[14:15], v[14:15], v[116:117]
	v_pk_mul_f32 v[10:11], v[10:11], v[176:177]
	v_pk_mul_f32 v[6:7], v[6:7], v[180:181]
	v_pk_mul_f32 v[2:3], v[2:3], v[184:185]
	v_pk_mul_f32 v[0:1], v[0:1], v[182:183]
	ds_read_b128 v[114:117], v242 offset:128
	s_waitcnt lgkmcnt(0)
	v_pk_mul_f32 v[64:65], v[64:65], v[114:115]
	v_pk_mul_f32 v[66:67], v[66:67], v[116:117]

; __device__ __forceinline__ void qkt8(f32x16& p0, f32x16& p1, const char* Ks, const i32x8* qf, int r32, int hi) {
;   p0 = f32x16{}; p1 = f32x16{};
;   const char* kb = Ks + r32 * K8ROW + hi * 32;
;   i32x8 a0 = ld32B(kb), a1 = ld32B(kb + 32 * K8ROW);
;   i32x8 b0 = ld32B(kb + 64), b1 = ld32B(kb + 32 * K8ROW + 64);
;   p0 = mfma8(a0, qf[0], p0); p1 = mfma8(a1, qf[0], p1);
;   a0 = ld32B(kb + 128); a1 = ld32B(kb + 32 * K8ROW + 128);
;   p0 = mfma8(b0, qf[1], p0); p1 = mfma8(b1, qf[1], p1);
;   p0 = mfma8(a0, qf[2], p0); p1 = mfma8(a1, qf[2], p1);
; }
; __device__ __forceinline__ void pv8(f32x16* o, f32x16& lacc, const char* Vs, i32x8 pf, int r32, int hi) {
;   const char* vb = Vs + r32 * V8ROW + hi * 32;
; #pragma unroll
;   for (int d0 = 0; d0 < 4; ++d0) o[d0] = mfma8(pf, ld32B(vb + d0 * 32 * V8ROW), o[d0]);
;   const int one4 = 0x38383838;
;   lacc = mfma8(pf, i32x8{one4, one4, one4, one4, one4, one4, one4, one4}, lacc);
; }
; __device__ __forceinline__ void partialSM8(f32x16& p0, f32x16& p1, float& m_reg, float& mn, float& alpha) {
;   float pmax = p0[0];
; #pragma unroll
;   for (int r = 1; r < 16; ++r) pmax = fmaxf(pmax, p0[r]);
; #pragma unroll
;   for (int r = 0; r < 16; ++r) pmax = fmaxf(pmax, p1[r]);
;   { auto rr = __builtin_amdgcn_permlane32_swap(__float_as_uint(pmax), __float_as_uint(pmax), false, false);
;     pmax = fmaxf(__uint_as_float(rr[0]), __uint_as_float(rr[1])); }
;   if (__builtin_expect(__all(pmax - m_reg <= THR8 * 8.f * 1.4426950408889634f), 1)) { mn = m_reg; alpha = 1.f; }
;   else { mn = fmaxf(m_reg, pmax); alpha = __builtin_amdgcn_exp2f((m_reg - mn) * 0.125f); m_reg = mn; }
;   const float mn8 = (P8SHIFT + 7.f - 0.0436f) * 8.f + 0.5f - mn;
; #pragma unroll
;   for (int r = 0; r < 16; ++r) p0[r] += mn8;
; #pragma unroll
;   for (int r = 0; r < 16; ++r) p1[r] += mn8;
; }
; __device__ __forceinline__ unsigned pk4u8(float a, float b, float c, float d) {
;   unsigned w = __builtin_amdgcn_cvt_pk_u8_f32(a, 0u, 0u); w = __builtin_amdgcn_cvt_pk_u8_f32(b, 1u, w);
;   w = __builtin_amdgcn_cvt_pk_u8_f32(c, 2u, w); return __builtin_amdgcn_cvt_pk_u8_f32(d, 3u, w);
; }
; __device__ __forceinline__ void finishSM8(f32x16& p0, f32x16& p1, i32x8& pf) {
; #pragma unroll
;   for (int w = 0; w < 4; ++w) { pf[w] = (int)pk4u8(p0[4 * w], p0[4 * w + 1], p0[4 * w + 2], p0[4 * w + 3]);
.LBB0_924:
	v_cndmask_b32_e64 v168, v172, v216, s[10:11]
	v_sub_f32_e32 v236, 0x42c04d6a, v168
	s_add_i32 s2, s22, 1
	s_and_b32 s2, s2, 3
	v_pk_add_f32 v[114:115], v[96:97], v[236:237] op_sel_hi:[1,0]
	v_pk_add_f32 v[116:117], v[98:99], v[236:237] op_sel_hi:[1,0]
	v_pk_add_f32 v[118:119], v[100:101], v[236:237] op_sel_hi:[1,0]
	v_pk_add_f32 v[186:187], v[102:103], v[236:237] op_sel_hi:[1,0]
	v_pk_add_f32 v[188:189], v[104:105], v[236:237] op_sel_hi:[1,0]
	v_pk_add_f32 v[190:191], v[106:107], v[236:237] op_sel_hi:[1,0]
	v_pk_add_f32 v[194:195], v[108:109], v[236:237] op_sel_hi:[1,0]
	v_pk_add_f32 v[196:197], v[110:111], v[236:237] op_sel_hi:[1,0]
	v_pk_add_f32 v[198:199], v[80:81], v[236:237] op_sel_hi:[1,0]
	v_pk_add_f32 v[202:203], v[82:83], v[236:237] op_sel_hi:[1,0]
	v_pk_add_f32 v[204:205], v[84:85], v[236:237] op_sel_hi:[1,0]
	v_pk_add_f32 v[226:227], v[86:87], v[236:237] op_sel_hi:[1,0]
	v_pk_add_f32 v[228:229], v[88:89], v[236:237] op_sel_hi:[1,0]
	v_pk_add_f32 v[230:231], v[90:91], v[236:237] op_sel_hi:[1,0]
	v_pk_add_f32 v[232:233], v[92:93], v[236:237] op_sel_hi:[1,0]
	v_pk_add_f32 v[234:235], v[94:95], v[236:237] op_sel_hi:[1,0]
	s_mulk_i32 s2, 0x3400
	v_add_u32_e32 v222, s2, v214
	ds_read_b128 v[80:83], v222 offset:51200
	ds_read_b128 v[84:87], v222 offset:51216
	v_cvt_pk_u8_f32 v114, v114, 0, 0
	v_cvt_pk_u8_f32 v114, v115, 1, v114
	v_cvt_pk_u8_f32 v114, v116, 2, v114
	s_waitcnt lgkmcnt(0)
	v_mfma_scale_f32_32x32x64_f8f6f4 v[96:111], v[80:87], v[120:127], 0, v193, v193 op_sel_hi:[0,0,0]
	ds_read_b128 v[80:83], v222 offset:57856
	ds_read_b128 v[84:87], v222 offset:57872
	ds_read_b128 v[170:173], v222 offset:51264
	ds_read_b128 v[174:177], v222 offset:51280
	s_waitcnt lgkmcnt(2)
	v_mfma_scale_f32_32x32x64_f8f6f4 v[80:95], v[80:87], v[120:127], 0, v193, v193 op_sel_hi:[0,0,0]
	s_waitcnt lgkmcnt(0)
	v_mfma_scale_f32_32x32x64_f8f6f4 v[96:111], v[170:177], v[128:135], v[96:111], v193, v193 op_sel_hi:[0,0,0]
	ds_read_b128 v[170:173], v222 offset:57920
	ds_read_b128 v[174:177], v222 offset:57936
	ds_read_b128 v[178:181], v222 offset:51328
	ds_read_b128 v[182:185], v222 offset:51344
	ds_read_b128 v[218:221], v222 offset:57984
	ds_read_b128 v[222:225], v222 offset:58000
	s_waitcnt lgkmcnt(4)
	v_mfma_scale_f32_32x32x64_f8f6f4 v[80:95], v[170:177], v[128:135], v[80:95], v193, v193 op_sel_hi:[0,0,0]
	v_cvt_pk_u8_f32 v172, v117, 3, v114
	v_cvt_pk_u8_f32 v114, v198, 0, 0
	v_cvt_pk_u8_f32 v114, v199, 1, v114
	v_cvt_pk_u8_f32 v114, v202, 2, v114
	v_cvt_pk_u8_f32 v176, v203, 3, v114
	v_cvt_pk_u8_f32 v114, v118, 0, 0
	v_cvt_pk_u8_f32 v114, v119, 1, v114
	v_cvt_pk_u8_f32 v114, v186, 2, v114
	v_cvt_pk_u8_f32 v173, v187, 3, v114
	v_cvt_pk_u8_f32 v114, v204, 0, 0
	v_cvt_pk_u8_f32 v114, v205, 1, v114
	v_cvt_pk_u8_f32 v114, v226, 2, v114
	v_cvt_pk_u8_f32 v177, v227, 3, v114
	v_cvt_pk_u8_f32 v114, v188, 0, 0
	v_cvt_pk_u8_f32 v114, v189, 1, v114
	s_waitcnt lgkmcnt(2)
	v_mfma_scale_f32_32x32x64_f8f6f4 v[96:111], v[178:185], v[136:143], v[96:111], v193, v193 op_sel_hi:[0,0,0]
	v_cvt_pk_u8_f32 v114, v190, 2, v114
	v_cvt_pk_u8_f32 v174, v191, 3, v114
	v_cvt_pk_u8_f32 v114, v228, 0, 0
	v_cvt_pk_u8_f32 v114, v229, 1, v114
	v_cvt_pk_u8_f32 v114, v230, 2, v114
	v_cvt_pk_u8_f32 v178, v231, 3, v114
	v_cvt_pk_u8_f32 v114, v194, 0, 0
	v_cvt_pk_u8_f32 v114, v195, 1, v114
	v_cvt_pk_u8_f32 v114, v196, 2, v114
	v_cvt_pk_u8_f32 v175, v197, 3, v114
	v_cvt_pk_u8_f32 v114, v232, 0, 0
	v_cvt_pk_u8_f32 v114, v233, 1, v114
	v_cvt_pk_u8_f32 v114, v234, 2, v114
	v_cvt_pk_u8_f32 v179, v235, 3, v114
	s_waitcnt lgkmcnt(0)
	v_mfma_scale_f32_32x32x64_f8f6f4 v[80:95], v[218:225], v[136:143], v[80:95], v193, v193 op_sel_hi:[0,0,0]
	s_mul_i32 s2, s16, 0x2800
	s_addk_i32 s2, 0xd800
	s_cmp_lg_u32 s16, 0
	s_cselect_b32 s2, s2, 0xa000
	v_add_u32_e32 v113, s2, v217
	ds_read_b128 v[180:183], v113
	ds_read_b128 v[184:187], v113 offset:16
	v_max_f32_e32 v169, v96, v97
	v_max3_f32 v169, v169, v98, v99
	v_max3_f32 v169, v169, v100, v101
	s_waitcnt lgkmcnt(0)
	v_mfma_scale_f32_32x32x64_f8f6f4 v[48:63], v[172:179], v[180:187], v[48:63], v193, v193 op_sel_hi:[0,0,0]
	ds_read_b128 v[180:183], v113 offset:2560
	ds_read_b128 v[184:187], v113 offset:2576
	v_max3_f32 v169, v169, v102, v103
	v_max3_f32 v169, v169, v104, v105
	v_max3_f32 v169, v169, v106, v107
	v_max3_f32 v169, v169, v108, v109
	v_max3_f32 v169, v169, v110, v111
	v_max3_f32 v169, v169, v80, v81
	v_max3_f32 v169, v169, v82, v83
	v_max3_f32 v169, v169, v84, v85
	v_max3_f32 v169, v169, v86, v87
	s_waitcnt lgkmcnt(0)
	v_mfma_scale_f32_32x32x64_f8f6f4 v[32:47], v[172:179], v[180:187], v[32:47], v193, v193 op_sel_hi:[0,0,0]
	ds_read_b128 v[180:183], v113 offset:5120
	ds_read_b128 v[184:187], v113 offset:5136
	ds_read_b128 v[218:221], v113 offset:7680
	ds_read_b128 v[222:225], v113 offset:7696
	v_max3_f32 v169, v169, v88, v89
	v_max3_f32 v169, v169, v90, v91
	v_max3_f32 v169, v169, v92, v93
	v_max3_f32 v169, v169, v94, v95
	v_mov_b32_e32 v170, v169
	s_nop 1
	v_permlane32_swap_b32_e32 v169, v170
	v_max_f32_e32 v169, v169, v170
	v_sub_f32_e32 v170, v169, v168
	v_cmp_ge_f32_e32 vcc, s61, v170
	s_waitcnt lgkmcnt(2)
	v_mfma_scale_f32_32x32x64_f8f6f4 v[16:31], v[172:179], v[180:187], v[16:31], v193, v193 op_sel_hi:[0,0,0]
	s_cmp_eq_u64 vcc, exec
	s_cselect_b64 s[10:11], -1, 0
	s_waitcnt lgkmcnt(0)
	v_mfma_scale_f32_32x32x64_f8f6f4 v[0:15], v[172:179], v[218:225], v[0:15], v193, v193 op_sel_hi:[0,0,0]
	v_mfma_scale_f32_16x16x128_f8f6f4 v[64:67], v[172:179], v[244:251], v[64:67], v193, v193 op_sel_hi:[0,0,0]
	s_cbranch_scc1 .LBB0_928
; __device__ __forceinline__ void partialSM8(f32x16& p0, f32x16& p1, float& m_reg, float& mn, float& alpha) {
;     ...
;   if (__builtin_expect(__all(pmax - m_reg <= THR8 * 8.f * 1.4426950408889634f), 1)) { mn = m_reg; alpha = 1.f; }
;   else { mn = fmaxf(m_reg, pmax); alpha = __builtin_amdgcn_exp2f((m_reg - mn) * 0.125f); m_reg = mn; }
	v_max_f32_e32 v169, v168, v169
	v_sub_f32_e32 v171, v168, v169
	v_mul_f32_e32 v171, 0x3e000000, v171
	v_exp_f32_e32 v171, v171
	s_nop 0
	v_mov_b32_e32 v170, v171
	v_cmp_gt_f32_e32 vcc, 1.0, v170
	s_cbranch_vccz .LBB0_928
	s_and_saveexec_b64 s[14:15], s[8:9]
	ds_write_b32 v215, v170 offset:128
	s_or_b64 exec, exec, s[14:15]
	s_waitcnt lgkmcnt(0)
	v_add_u32_e32 v113, v159, v213
	ds_read_b128 v[114:117], v113 offset:224
	ds_read_b128 v[170:173], v113 offset:192
	ds_read_b128 v[174:177], v113 offset:160
	ds_read_b128 v[178:181], v113 offset:128
	s_waitcnt lgkmcnt(3)
	v_pk_mul_f32 v[60:61], v[60:61], v[114:115]
	s_waitcnt lgkmcnt(2)
	v_pk_mul_f32 v[56:57], v[56:57], v[170:171]
	s_waitcnt lgkmcnt(1)
	v_pk_mul_f32 v[52:53], v[52:53], v[174:175]
	v_pk_mul_f32 v[62:63], v[62:63], v[116:117]
	v_pk_mul_f32 v[58:59], v[58:59], v[172:173]
	v_pk_mul_f32 v[54:55], v[54:55], v[176:177]
	s_waitcnt lgkmcnt(0)
	v_pk_mul_f32 v[50:51], v[50:51], v[180:181]
	v_pk_mul_f32 v[48:49], v[48:49], v[178:179]
	v_pk_mul_f32 v[44:45], v[44:45], v[114:115]
	v_pk_mul_f32 v[40:41], v[40:41], v[170:171]
	v_pk_mul_f32 v[36:37], v[36:37], v[174:175]
	v_pk_mul_f32 v[46:47], v[46:47], v[116:117]
	v_pk_mul_f32 v[42:43], v[42:43], v[172:173]
	v_pk_mul_f32 v[38:39], v[38:39], v[176:177]
	v_pk_mul_f32 v[34:35], v[34:35], v[180:181]
	v_pk_mul_f32 v[32:33], v[32:33], v[178:179]
	v_pk_mul_f32 v[28:29], v[28:29], v[114:115]
	v_pk_mul_f32 v[24:25], v[24:25], v[170:171]
	v_pk_mul_f32 v[20:21], v[20:21], v[174:175]
	v_pk_mul_f32 v[30:31], v[30:31], v[116:117]
	v_pk_mul_f32 v[26:27], v[26:27], v[172:173]
	v_pk_mul_f32 v[22:23], v[22:23], v[176:177]
	v_pk_mul_f32 v[18:19], v[18:19], v[180:181]
	v_pk_mul_f32 v[16:17], v[16:17], v[178:179]
	v_pk_mul_f32 v[12:13], v[12:13], v[114:115]
	v_pk_mul_f32 v[8:9], v[8:9], v[170:171]
	v_pk_mul_f32 v[4:5], v[4:5], v[174:175]
	v_pk_mul_f32 v[14:15], v[14:15], v[116:117]
	v_pk_mul_f32 v[10:11], v[10:11], v[172:173]
	v_pk_mul_f32 v[6:7], v[6:7], v[176:177]
	v_pk_mul_f32 v[2:3], v[2:3], v[180:181]
	v_pk_mul_f32 v[0:1], v[0:1], v[178:179]
	ds_read_b128 v[114:117], v242 offset:128
	s_waitcnt lgkmcnt(0)
	v_pk_mul_f32 v[64:65], v[64:65], v[114:115]
	v_pk_mul_f32 v[66:67], v[66:67], v[116:117]
